# V fragments preloaded also in NSA window and compressed branch loops
# baseline (speedup 1.0000x reference)
; #define MFMA(a, b, c) __builtin_amdgcn_mfma_f32_32x32x16_f16(__builtin_bit_cast(h16x8, (a)), __builtin_bit_cast(h16x8, (b)), (c), 0, 0, 0)
; DI unsigned pk2(float a, float b) { f2_t v = {a, b}; bf2_t r = __builtin_convertvector(v, bf2_t); return __builtin_bit_cast(unsigned, r); }
; template <int MODE> ...
;     ...
;             const float mc = m[nb];
;             float ps = 0.f;
; #pragma unroll
;             for (int i = 0; i < 16; ++i) {
;               sv[i] = __builtin_amdgcn_exp2f(sv[i] - mc);
;               ps += sv[i];
;             }
;             l[nb] += ps;
; #pragma unroll
;             for (int s2 = 0; s2 < 2; ++s2) {
;               const unsigned u0 = pk2(sv[8 * s2], sv[8 * s2 + 1]), u1 = pk2(sv[8 * s2 + 2], sv[8 * s2 + 3]);
;               const unsigned u2 = pk2(sv[8 * s2 + 4], sv[8 * s2 + 5]), u3 = pk2(sv[8 * s2 + 6], sv[8 * s2 + 7]);
;               const uint4 uu = make_uint4(u0, u1, u2, u3);
;               pk[nb][s2] = __builtin_bit_cast(bf16x8, uu);
;             }
;           }
;         }
;         if (MODE != M_CMP2) {
; #pragma unroll
;           for (int s2 = 0; s2 < 2; ++s2) {
; #pragma unroll
;             for (int db = 0; db < 2; ++db) {
;               const u16* vp = Vt + (kb * 32 + 16 * s2 + 4 * h + q4) * LDK + db * 32 + 16 * blk + 4 * p4;
;               const s16x4 lo = __builtin_amdgcn_ds_read_tr16_b64_v4i16((__attribute__((address_space(3))) s16x4*)(vp));
;               const s16x4 hi = __builtin_amdgcn_ds_read_tr16_b64_v4i16((__attribute__((address_space(3))) s16x4*)(vp + 8 * LDK));
;               const bf16x8 a = __builtin_shufflevector(lo, hi, 0, 1, 2, 3, 4, 5, 6, 7);
;               O[db][0] = MFMA(a, pk[0][s2], O[db][0]);
;               O[db][1] = MFMA(a, pk[1][s2], O[db][1]);
;             }
;           }
;         }
.LBB0_673:
	v_or_b32_e32 v244, s46, v166
	v_mad_u32_u24 v244, v244, s76, v15
	ds_read_b64_tr_b16 v[228:229], v244 offset:18432
	ds_read_b64_tr_b16 v[230:231], v244 offset:19584
	ds_read_b64_tr_b16 v[232:233], v244 offset:18496
	ds_read_b64_tr_b16 v[234:235], v244 offset:19648
	ds_read_b64_tr_b16 v[236:237], v244 offset:20736
	ds_read_b64_tr_b16 v[238:239], v244 offset:21888
	ds_read_b64_tr_b16 v[240:241], v244 offset:20800
	ds_read_b64_tr_b16 v[242:243], v244 offset:21952
	v_sub_f32_e32 v2, v190, v160
	v_exp_f32_e32 v2, v2
	v_sub_f32_e32 v4, v189, v160
	v_exp_f32_e32 v4, v4
	v_sub_f32_e32 v5, v188, v160
	v_exp_f32_e32 v5, v5
	v_sub_f32_e32 v10, v187, v160
	v_exp_f32_e32 v11, v10
	v_sub_f32_e32 v10, v186, v160
	v_add_f32_e32 v3, 0, v2
	v_exp_f32_e32 v12, v10
	v_sub_f32_e32 v10, v183, v160
	v_add_f32_e32 v3, v4, v3
	v_exp_f32_e32 v13, v10
	v_sub_f32_e32 v10, v184, v160
	v_add_f32_e32 v3, v5, v3
	v_exp_f32_e32 v92, v10
	v_sub_f32_e32 v10, v185, v160
	v_sub_f32_e32 v6, v6, v159
	v_add_f32_e32 v3, v11, v3
	v_exp_f32_e32 v93, v10
	v_exp_f32_e32 v6, v6
	v_sub_f32_e32 v7, v7, v159
	v_add_f32_e32 v3, v12, v3
	v_sub_f32_e32 v10, v176, v160
	v_exp_f32_e32 v7, v7
	v_sub_f32_e32 v8, v8, v159
	v_add_f32_e32 v3, v13, v3
	v_exp_f32_e32 v94, v10
	v_sub_f32_e32 v10, v180, v160
	v_exp_f32_e32 v8, v8
	v_sub_f32_e32 v9, v9, v159
	v_add_f32_e32 v3, v92, v3
	v_exp_f32_e32 v95, v10
	v_sub_f32_e32 v10, v181, v160
	v_exp_f32_e32 v9, v9
	v_sub_f32_e32 v80, v80, v159
	v_add_f32_e32 v3, v93, v3
	v_exp_f32_e32 v144, v10
	v_sub_f32_e32 v10, v182, v160
	v_cvt_pk_f16_f32 v12, v12, v13
	v_cvt_pk_f16_f32 v13, v92, v93
	v_add_f32_e32 v92, 0, v6
	v_exp_f32_e32 v93, v80
	v_exp_f32_e32 v145, v10
	v_sub_f32_e32 v10, v170, v160
	v_add_f32_e32 v92, v7, v92
	v_exp_f32_e32 v146, v10
	v_sub_f32_e32 v10, v171, v160
	v_add_f32_e32 v92, v8, v92
	v_exp_f32_e32 v147, v10
	v_sub_f32_e32 v10, v174, v160
	v_add_f32_e32 v92, v9, v92
	v_sub_f32_e32 v81, v81, v159
	v_exp_f32_e32 v170, v10
	v_sub_f32_e32 v10, v175, v160
	v_add_f32_e32 v80, v93, v92
	v_exp_f32_e32 v92, v81
	v_sub_f32_e32 v81, v82, v159
	v_add_f32_e32 v3, v94, v3
	v_exp_f32_e32 v171, v10
	v_cvt_pk_f16_f32 v10, v2, v4
	v_cvt_pk_f16_f32 v2, v94, v95
	v_exp_f32_e32 v94, v81
	v_sub_f32_e32 v81, v83, v159
	v_exp_f32_e32 v83, v81
	v_sub_f32_e32 v81, v84, v159
	v_exp_f32_e32 v84, v81
	v_sub_f32_e32 v81, v85, v159
	v_add_f32_e32 v80, v92, v80
	v_exp_f32_e32 v85, v81
	v_sub_f32_e32 v81, v86, v159
	v_add_f32_e32 v80, v94, v80
	v_exp_f32_e32 v86, v81
	v_sub_f32_e32 v81, v87, v159
	v_add_f32_e32 v80, v83, v80
	v_exp_f32_e32 v87, v81
	v_sub_f32_e32 v81, v88, v159
	v_add_f32_e32 v80, v84, v80
	v_exp_f32_e32 v88, v81
	v_sub_f32_e32 v81, v89, v159
	v_add_f32_e32 v80, v85, v80
	v_exp_f32_e32 v89, v81
	v_sub_f32_e32 v81, v90, v159
	v_add_f32_e32 v80, v86, v80
	v_exp_f32_e32 v90, v81
	v_sub_f32_e32 v81, v91, v159
	v_add_f32_e32 v80, v87, v80
	v_exp_f32_e32 v91, v81
	v_add_f32_e32 v80, v88, v80
	v_add_f32_e32 v80, v89, v80
	v_add_f32_e32 v80, v90, v80
	v_add_f32_e32 v80, v91, v80
	v_add_f32_e32 v161, v161, v80
	v_cvt_pk_f16_f32 v80, v6, v7
	v_cvt_pk_f16_f32 v6, v84, v85
	v_or_b32_e32 v84, s46, v166
	v_cvt_pk_f16_f32 v81, v8, v9
	v_cvt_pk_f16_f32 v8, v88, v89
	v_mad_u32_u24 v88, v84, s76, v15
	v_cvt_pk_f16_f32 v7, v86, v87
	v_cvt_pk_f16_f32 v11, v5, v11
	v_cvt_pk_f16_f32 v82, v93, v92
	v_cvt_pk_f16_f32 v83, v94, v83
	s_waitcnt lgkmcnt(0)
	v_mfma_f32_32x32x16_f16 v[64:79], v[228:231], v[10:13], v[64:79]
	v_add_f32_e32 v3, v95, v3
	v_add_f32_e32 v3, v144, v3
	v_add_f32_e32 v3, v145, v3
	v_add_f32_e32 v3, v146, v3
	v_add_f32_e32 v3, v147, v3
	v_add_f32_e32 v3, v170, v3
	v_add_f32_e32 v3, v171, v3
	v_mfma_f32_32x32x16_f16 v[32:47], v[228:231], v[80:83], v[32:47]
	v_add_f32_e32 v14, v14, v3
	v_cvt_pk_f16_f32 v3, v144, v145
	v_cvt_pk_f16_f32 v4, v146, v147
	v_cvt_pk_f16_f32 v5, v170, v171
	v_cvt_pk_f16_f32 v9, v90, v91
	s_waitcnt lgkmcnt(0)
	v_mfma_f32_32x32x16_f16 v[48:63], v[232:235], v[10:13], v[48:63]
	v_mfma_f32_32x32x16_f16 v[16:31], v[232:235], v[80:83], v[16:31]
	s_waitcnt lgkmcnt(0)
	v_mfma_f32_32x32x16_f16 v[64:79], v[236:239], v[2:5], v[64:79]
	v_mfma_f32_32x32x16_f16 v[32:47], v[236:239], v[6:9], v[32:47]
	s_waitcnt lgkmcnt(0)
	v_mfma_f32_32x32x16_f16 v[48:63], v[240:243], v[2:5], v[48:63]
	v_mov_b32_e32 v2, v14
	v_mfma_f32_32x32x16_f16 v[16:31], v[240:243], v[6:9], v[16:31]

; #define MFMA(a, b, c) __builtin_amdgcn_mfma_f32_32x32x16_f16(__builtin_bit_cast(h16x8, (a)), __builtin_bit_cast(h16x8, (b)), (c), 0, 0, 0)
; DI unsigned pk2(float a, float b) { f2_t v = {a, b}; bf2_t r = __builtin_convertvector(v, bf2_t); return __builtin_bit_cast(unsigned, r); }
; template <int MODE> ...
;     ...
;             const float mc = m[nb];
;             float ps = 0.f;
; #pragma unroll
;             for (int i = 0; i < 16; ++i) {
;               sv[i] = __builtin_amdgcn_exp2f(sv[i] - mc);
;               ps += sv[i];
;             }
;             l[nb] += ps;
; #pragma unroll
;             for (int s2 = 0; s2 < 2; ++s2) {
;               const unsigned u0 = pk2(sv[8 * s2], sv[8 * s2 + 1]), u1 = pk2(sv[8 * s2 + 2], sv[8 * s2 + 3]);
;               const unsigned u2 = pk2(sv[8 * s2 + 4], sv[8 * s2 + 5]), u3 = pk2(sv[8 * s2 + 6], sv[8 * s2 + 7]);
;               const uint4 uu = make_uint4(u0, u1, u2, u3);
;               pk[nb][s2] = __builtin_bit_cast(bf16x8, uu);
;             }
;           }
;         }
;         if (MODE != M_CMP2) {
; #pragma unroll
;           for (int s2 = 0; s2 < 2; ++s2) {
; #pragma unroll
;             for (int db = 0; db < 2; ++db) {
;               const u16* vp = Vt + (kb * 32 + 16 * s2 + 4 * h + q4) * LDK + db * 32 + 16 * blk + 4 * p4;
;               const s16x4 lo = __builtin_amdgcn_ds_read_tr16_b64_v4i16((__attribute__((address_space(3))) s16x4*)(vp));
;               const s16x4 hi = __builtin_amdgcn_ds_read_tr16_b64_v4i16((__attribute__((address_space(3))) s16x4*)(vp + 8 * LDK));
;               const bf16x8 a = __builtin_shufflevector(lo, hi, 0, 1, 2, 3, 4, 5, 6, 7);
;               O[db][0] = MFMA(a, pk[0][s2], O[db][0]);
;               O[db][1] = MFMA(a, pk[1][s2], O[db][1]);
;             }
;           }
;         }
.LBB0_753:
	v_or_b32_e32 v244, s20, v184
	v_mad_u32_u24 v244, v244, s76, v189
	ds_read_b64_tr_b16 v[228:229], v244 offset:18432
	ds_read_b64_tr_b16 v[230:231], v244 offset:19584
	ds_read_b64_tr_b16 v[232:233], v244 offset:18496
	ds_read_b64_tr_b16 v[234:235], v244 offset:19648
	ds_read_b64_tr_b16 v[236:237], v244 offset:20736
	ds_read_b64_tr_b16 v[238:239], v244 offset:21888
	ds_read_b64_tr_b16 v[240:241], v244 offset:20800
	ds_read_b64_tr_b16 v[242:243], v244 offset:21952
	v_sub_f32_e32 v2, v80, v15
	v_exp_f32_e32 v2, v2
	v_sub_f32_e32 v4, v81, v15
	v_exp_f32_e32 v4, v4
	v_sub_f32_e32 v5, v82, v15
	v_exp_f32_e32 v5, v5
	v_sub_f32_e32 v6, v83, v15
	v_exp_f32_e32 v6, v6
	v_sub_f32_e32 v7, v84, v15
	v_add_f32_e32 v3, 0, v2
	v_exp_f32_e32 v7, v7
	v_sub_f32_e32 v8, v85, v15
	v_add_f32_e32 v3, v4, v3
	v_exp_f32_e32 v8, v8
	v_sub_f32_e32 v9, v86, v15
	v_add_f32_e32 v3, v5, v3
	v_exp_f32_e32 v9, v9
	v_sub_f32_e32 v10, v87, v15
	v_add_f32_e32 v3, v6, v3
	v_exp_f32_e32 v13, v10
	v_sub_f32_e32 v10, v88, v15
	v_add_f32_e32 v3, v7, v3
	v_exp_f32_e32 v80, v10
	v_sub_f32_e32 v10, v89, v15
	v_add_f32_e32 v3, v8, v3
	v_exp_f32_e32 v81, v10
	v_sub_f32_e32 v10, v90, v15
	v_add_f32_e32 v3, v9, v3
	v_exp_f32_e32 v82, v10
	v_sub_f32_e32 v10, v91, v15
	v_add_f32_e32 v3, v13, v3
	v_exp_f32_e32 v83, v10
	v_sub_f32_e32 v10, v92, v15
	v_add_f32_e32 v3, v80, v3
	v_exp_f32_e32 v84, v10
	v_sub_f32_e32 v10, v93, v15
	v_add_f32_e32 v3, v81, v3
	v_exp_f32_e32 v85, v10
	v_sub_f32_e32 v10, v94, v15
	v_add_f32_e32 v3, v82, v3
	v_exp_f32_e32 v86, v10
	v_sub_f32_e32 v10, v95, v15
	v_add_f32_e32 v3, v83, v3
	v_exp_f32_e32 v87, v10
	v_cvt_pk_f16_f32 v11, v5, v6
	v_sub_f32_e32 v6, v96, v188
	v_add_f32_e32 v3, v84, v3
	v_cvt_pk_f16_f32 v12, v7, v8
	v_exp_f32_e32 v6, v6
	v_sub_f32_e32 v8, v97, v188
	v_add_f32_e32 v3, v85, v3
	v_cvt_pk_f16_f32 v13, v9, v13
	v_exp_f32_e32 v8, v8
	v_sub_f32_e32 v9, v98, v188
	v_add_f32_e32 v3, v86, v3
	v_cvt_pk_f16_f32 v10, v2, v4
	v_cvt_pk_f16_f32 v2, v80, v81
	v_exp_f32_e32 v9, v9
	v_sub_f32_e32 v80, v99, v188
	v_add_f32_e32 v3, v87, v3
	v_exp_f32_e32 v81, v80
	v_sub_f32_e32 v80, v100, v188
	v_add_f32_e32 v14, v14, v3
	v_cvt_pk_f16_f32 v3, v82, v83
	v_add_f32_e32 v7, 0, v6
	v_exp_f32_e32 v82, v80
	v_sub_f32_e32 v80, v101, v188
	v_add_f32_e32 v7, v8, v7
	v_exp_f32_e32 v83, v80
	v_sub_f32_e32 v80, v102, v188
	v_cvt_pk_f16_f32 v4, v84, v85
	v_add_f32_e32 v7, v9, v7
	v_exp_f32_e32 v84, v80
	v_sub_f32_e32 v80, v103, v188
	v_add_f32_e32 v7, v81, v7
	v_exp_f32_e32 v85, v80
	v_sub_f32_e32 v80, v104, v188
	v_cvt_pk_f16_f32 v5, v86, v87
	v_add_f32_e32 v7, v82, v7
	v_exp_f32_e32 v86, v80
	v_sub_f32_e32 v80, v105, v188
	v_add_f32_e32 v7, v83, v7
	v_exp_f32_e32 v87, v80
	v_sub_f32_e32 v80, v106, v188
	v_add_f32_e32 v7, v84, v7
	v_exp_f32_e32 v88, v80
	v_sub_f32_e32 v80, v107, v188
	v_add_f32_e32 v7, v85, v7
	v_exp_f32_e32 v89, v80
	v_sub_f32_e32 v80, v108, v188
	v_add_f32_e32 v7, v86, v7
	v_exp_f32_e32 v90, v80
	v_sub_f32_e32 v80, v109, v188
	v_add_f32_e32 v7, v87, v7
	v_exp_f32_e32 v91, v80
	v_sub_f32_e32 v80, v110, v188
	v_add_f32_e32 v7, v88, v7
	v_exp_f32_e32 v92, v80
	v_sub_f32_e32 v80, v111, v188
	v_add_f32_e32 v7, v89, v7
	v_exp_f32_e32 v93, v80
	v_add_f32_e32 v7, v90, v7
	v_add_f32_e32 v7, v91, v7
	v_add_f32_e32 v7, v92, v7
	v_add_f32_e32 v7, v93, v7
	v_cvt_pk_f16_f32 v82, v82, v83
	v_cvt_pk_f16_f32 v83, v84, v85
	v_or_b32_e32 v84, s20, v184
	v_add_f32_e32 v164, v164, v7
	v_cvt_pk_f16_f32 v7, v88, v89
	v_mad_u32_u24 v88, v84, s76, v189
	v_cvt_pk_f16_f32 v80, v6, v8
	v_cvt_pk_f16_f32 v6, v86, v87
	v_cvt_pk_f16_f32 v81, v9, v81
	s_waitcnt lgkmcnt(0)
	v_mfma_f32_32x32x16_f16 v[64:79], v[228:231], v[10:13], v[64:79]
	v_cvt_pk_f16_f32 v8, v90, v91
	v_cvt_pk_f16_f32 v9, v92, v93
	v_mfma_f32_32x32x16_f16 v[32:47], v[228:231], v[80:83], v[32:47]
	s_waitcnt lgkmcnt(0)
	v_mfma_f32_32x32x16_f16 v[48:63], v[232:235], v[10:13], v[48:63]
	v_mfma_f32_32x32x16_f16 v[16:31], v[232:235], v[80:83], v[16:31]
	s_waitcnt lgkmcnt(0)
	v_mfma_f32_32x32x16_f16 v[64:79], v[236:239], v[2:5], v[64:79]
	v_mfma_f32_32x32x16_f16 v[32:47], v[236:239], v[6:9], v[32:47]
	s_waitcnt lgkmcnt(0)
	v_mfma_f32_32x32x16_f16 v[48:63], v[240:243], v[2:5], v[48:63]
	v_mov_b32_e32 v2, v14
	v_mfma_f32_32x32x16_f16 v[16:31], v[240:243], v[6:9], v[16:31]
